# MLA-up tile loop: weight-tile LDS store addresses (software divide, 3 integer multiplies per piece) computed once per part instead of every tile
# baseline (speedup 1.0000x reference)
; DI float bf2f(u16 b) { return __uint_as_float(((unsigned)b) << 16); }
; DI int crow(int r, int hh) { return (r & 3) + 8 * (r >> 2) + 4 * hh; }
; DI void phase_mla_up(const Params& p, int layer, char* lds) {
;     ...
;       const int K = part == 0 ? 192 : 128, acol = part == 0 ? C_CQ : C_CKV, STR = (K + 8) * 2, CPR = K / 8;
;       const int NCT = part == 0 ? 9 : 12;
;       const u16* Wt = part == 0 ? wuq : wukv;
;       __syncthreads();
;       for (int c = tid; c < 128 * CPR; c += NTHR) { int row = c / CPR, ch = c % CPR;
;         *(u32x4*)(As + row * STR + ch * 16) = *(const u32x4*)(H + (size_t)(m0 + row) * DIN + acol + ch * 8); }
;       __syncthreads();
;       {
;         int row = tid >> 2, part4 = tid & 3, n = K / 4; float ss = 0.f;
;         const u16* ar = (const u16*)(As + row * STR) + part4 * n;
;         for (int i = 0; i < n; ++i) { float v = bf2f(ar[i]); ss += v * v; }
;         ss += __shfl_xor(ss, 1); ss += __shfl_xor(ss, 2);
;         if (part4 == 0) rinv[row] = rsqrtf(ss / (float)K + 1e-6f);
;       }
;       const int NCT2 = (NCT + 1) / 2, NOUT = NCT * 64;
;       u32x4 rw[6];
;       auto wload = [&](int ct) {
;         int tl = tid; asm volatile("" : "+v"(tl));
; #pragma unroll
;         for (int i = 0; i < 6; ++i) { const int c = tl + NTHR * i; if (c < 128 * CPR) rw[i] = *(const u32x4*)(Wt + (size_t)ct * 128 * K + c * 8); }
;       };
;       __syncthreads();
;       float rv[16];
; #pragma unroll
;       for (int r = 0; r < 16; ++r) rv[r] = rinv[32 * wm + crow(r, hh)] * (part == 0 ? QSC : 1.f);
;       const int rowb = m0 + 32 * wm + 4 * hh;
;     ...
;           int tl = tid; asm volatile("" : "+v"(tl));
; #pragma unroll
;           for (int i = 0; i < 6; ++i) { const int c = tl + NTHR * i, row = c / CPR, ch = c % CPR; if (c < 128 * CPR) *(u32x4*)(Bs + row * STR + ch * 16) = rw[i]; }
.LBB0_188:
	s_or_b64 exec, exec, s[26:27]
	v_cndmask_b32_e64 v4, 1.0, v217, s[12:13]
	s_waitcnt lgkmcnt(3)
	v_mul_f32_e32 v95, v4, v18
	v_mul_f32_e32 v96, v4, v19
	v_mul_f32_e32 v97, v4, v20
	v_mul_f32_e32 v98, v4, v21
	s_waitcnt lgkmcnt(2)
	v_mul_f32_e32 v99, v4, v14
	v_mul_f32_e32 v100, v4, v15
	v_mul_f32_e32 v101, v4, v16
	v_mul_f32_e32 v102, v4, v17
	s_waitcnt lgkmcnt(1)
	v_mul_f32_e32 v103, v4, v10
	v_mul_f32_e32 v104, v4, v11
	v_mul_f32_e32 v105, v4, v12
	v_mul_f32_e32 v106, v4, v13
	s_waitcnt lgkmcnt(0)
	v_mul_f32_e32 v107, v4, v6
	v_mul_f32_e32 v108, v4, v7
	v_mul_f32_e32 v109, v4, v8
	v_mul_f32_e32 v110, v4, v9
	v_mul_f32_e32 v4, 0x4f7ffffe, v22
	v_cvt_u32_f32_e32 v4, v4
	s_and_b64 s[26:27], s[12:13], exec
	s_cselect_b32 s26, 9, 12
	s_add_i32 s27, s26, 1
	s_sub_i32 s12, 0, s29
	s_lshr_b32 s77, s27, 1
	s_lshl_b32 s73, s26, 6
	v_mul_lo_u32 v6, s12, v4
	s_lshl_b32 s49, s49, 8
	v_mul_hi_u32 v6, v4, v6
	s_add_u32 s24, s24, s49
	s_mov_b32 s53, 0
	v_add_u32_e32 v111, v4, v6
	s_addc_u32 s25, s25, 0
	v_mov_b32_e32 v78, v89
	v_mov_b32_e32 v4, v59
	v_sub_u32_e32 v7, 0, v4
	v_max_i32_e32 v7, v4, v7
	v_mul_hi_u32 v8, v7, v111
	v_mul_lo_u32 v9, v8, s29
	v_sub_u32_e32 v7, v7, v9
	v_add_u32_e32 v9, 1, v8
	v_cmp_le_u32_e32 vcc, s29, v7
	v_ashrrev_i32_e32 v6, 31, v4
	s_nop 0
	v_cndmask_b32_e32 v8, v8, v9, vcc
	v_subrev_u32_e32 v9, s29, v7
	v_cndmask_b32_e32 v7, v7, v9, vcc
	v_add_u32_e32 v9, 1, v8
	v_cmp_le_u32_e32 vcc, s29, v7
	s_nop 1
	v_cndmask_b32_e32 v7, v8, v9, vcc
	v_xor_b32_e32 v7, v7, v6
	v_sub_u32_e32 v6, v7, v6
	v_mul_lo_u32 v7, v6, s29
	v_sub_u32_e32 v7, v4, v7
	v_mul_lo_u32 v6, v6, s76
	v_lshlrev_b32_e32 v7, 4, v7
	v_add3_u32 v6, 0, v6, v7
	v_mov_b32_e32 v148, v6
	v_add_u32_e32 v6, 0x200, v4
	v_sub_u32_e32 v8, 0, v6
	v_max_i32_e32 v8, v6, v8
	v_mul_hi_u32 v9, v8, v111
	v_mul_lo_u32 v10, v9, s29
	v_sub_u32_e32 v8, v8, v10
	v_add_u32_e32 v10, 1, v9
	v_cmp_le_u32_e32 vcc, s29, v8
	v_ashrrev_i32_e32 v7, 31, v6
	s_nop 0
	v_cndmask_b32_e32 v9, v9, v10, vcc
	v_subrev_u32_e32 v10, s29, v8
	v_cndmask_b32_e32 v8, v8, v10, vcc
	v_add_u32_e32 v10, 1, v9
	v_cmp_le_u32_e32 vcc, s29, v8
	s_nop 1
	v_cndmask_b32_e32 v8, v9, v10, vcc
	v_xor_b32_e32 v8, v8, v7
	v_sub_u32_e32 v7, v8, v7
	v_mul_lo_u32 v8, v7, s29
	v_sub_u32_e32 v6, v6, v8
	v_mul_lo_u32 v7, v7, s76
	v_lshlrev_b32_e32 v6, 4, v6
	v_add3_u32 v6, 0, v7, v6
	v_mov_b32_e32 v191, v6
	v_add_u32_e32 v6, 0x400, v4
	v_sub_u32_e32 v8, 0, v6
	v_max_i32_e32 v8, v6, v8
	v_mul_hi_u32 v9, v8, v111
	v_mul_lo_u32 v10, v9, s29
	v_sub_u32_e32 v8, v8, v10
	v_add_u32_e32 v10, 1, v9
	v_cmp_le_u32_e32 vcc, s29, v8
	v_ashrrev_i32_e32 v7, 31, v6
	s_nop 0
	v_cndmask_b32_e32 v9, v9, v10, vcc
	v_subrev_u32_e32 v10, s29, v8
	v_cndmask_b32_e32 v8, v8, v10, vcc
	v_add_u32_e32 v10, 1, v9
	v_cmp_le_u32_e32 vcc, s29, v8
	s_nop 1
	v_cndmask_b32_e32 v8, v9, v10, vcc
	v_xor_b32_e32 v8, v8, v7
	v_sub_u32_e32 v7, v8, v7
	v_mul_lo_u32 v8, v7, s29
	v_sub_u32_e32 v6, v6, v8
	v_mul_lo_u32 v7, v7, s76
	v_lshlrev_b32_e32 v6, 4, v6
	v_add3_u32 v6, 0, v7, v6
	v_mov_b32_e32 v200, v6
	v_add_u32_e32 v6, 0x600, v4
	v_sub_u32_e32 v8, 0, v6
	v_max_i32_e32 v8, v6, v8
	v_mul_hi_u32 v9, v8, v111
	v_mul_lo_u32 v10, v9, s29
	v_sub_u32_e32 v8, v8, v10
	v_add_u32_e32 v10, 1, v9
	v_cmp_le_u32_e32 vcc, s29, v8
	v_ashrrev_i32_e32 v7, 31, v6
	s_nop 0
	v_cndmask_b32_e32 v9, v9, v10, vcc
	v_subrev_u32_e32 v10, s29, v8
	v_cndmask_b32_e32 v8, v8, v10, vcc
	v_add_u32_e32 v10, 1, v9
	v_cmp_le_u32_e32 vcc, s29, v8
	s_nop 1
	v_cndmask_b32_e32 v8, v9, v10, vcc
	v_xor_b32_e32 v8, v8, v7
	v_sub_u32_e32 v7, v8, v7
	v_mul_lo_u32 v8, v7, s29
	v_sub_u32_e32 v6, v6, v8
	v_mul_lo_u32 v7, v7, s76
	v_lshlrev_b32_e32 v6, 4, v6
	v_add3_u32 v6, 0, v7, v6
	v_mov_b32_e32 v201, v6
	v_add_u32_e32 v6, 0x800, v4
	v_sub_u32_e32 v8, 0, v6
	v_max_i32_e32 v8, v6, v8
	v_mul_hi_u32 v9, v8, v111
	v_mul_lo_u32 v10, v9, s29
	v_sub_u32_e32 v8, v8, v10
	v_add_u32_e32 v10, 1, v9
	v_cmp_le_u32_e32 vcc, s29, v8
	v_ashrrev_i32_e32 v7, 31, v6
	s_nop 0
	v_cndmask_b32_e32 v9, v9, v10, vcc
	v_subrev_u32_e32 v10, s29, v8
	v_cndmask_b32_e32 v8, v8, v10, vcc
	v_add_u32_e32 v10, 1, v9
	v_cmp_le_u32_e32 vcc, s29, v8
	s_nop 1
	v_cndmask_b32_e32 v8, v9, v10, vcc
	v_xor_b32_e32 v8, v8, v7
	v_sub_u32_e32 v7, v8, v7
	v_mul_lo_u32 v8, v7, s29
	v_sub_u32_e32 v6, v6, v8
	v_mul_lo_u32 v7, v7, s76
	v_lshlrev_b32_e32 v6, 4, v6
	v_add3_u32 v6, 0, v7, v6
	v_mov_b32_e32 v208, v6
	v_add_u32_e32 v4, 0xa00, v4
	v_sub_u32_e32 v7, 0, v4
	v_max_i32_e32 v7, v4, v7
	v_mul_hi_u32 v8, v7, v111
	v_mul_lo_u32 v9, v8, s29
	v_sub_u32_e32 v7, v7, v9
	v_add_u32_e32 v9, 1, v8
	v_cmp_le_u32_e32 vcc, s29, v7
	v_ashrrev_i32_e32 v6, 31, v4
	s_nop 0
	v_cndmask_b32_e32 v8, v8, v9, vcc
	v_subrev_u32_e32 v9, s29, v7
	v_cndmask_b32_e32 v7, v7, v9, vcc
	v_add_u32_e32 v9, 1, v8
	v_cmp_le_u32_e32 vcc, s29, v7
	s_nop 1
	v_cndmask_b32_e32 v7, v8, v9, vcc
	v_xor_b32_e32 v7, v7, v6
	v_sub_u32_e32 v6, v7, v6
	v_mul_lo_u32 v7, v6, s29
	v_sub_u32_e32 v4, v4, v7
	v_mul_lo_u32 v6, v6, s76
	v_lshlrev_b32_e32 v4, 4, v4
	v_add3_u32 v4, 0, v6, v4
	v_mov_b32_e32 v209, v4
	s_branch .LBB0_191

; #define LDS_BARRIER() asm volatile("s_waitcnt lgkmcnt(0)\n\ts_barrier" ::: "memory")
; DI void phase_mla_up(const Params& p, int layer, char* lds) {
;     ...
;         {
;           int tl = tid; asm volatile("" : "+v"(tl));
; #pragma unroll
;           for (int i = 0; i < 6; ++i) { const int c = tl + NTHR * i, row = c / CPR, ch = c % CPR; if (c < 128 * CPR) *(u32x4*)(Bs + row * STR + ch * 16) = rw[i]; }
;         }
;         LDS_BARRIER();
.LBB0_191:
	v_mov_b32_e32 v4, v59
	s_nop 0
	v_cmp_gt_i32_e32 vcc, s93, v4
	s_and_saveexec_b64 s[12:13], vcc
	s_cbranch_execz .LBB0_193
	s_waitcnt vmcnt(0)
	ds_write_b128 v148, v[0:3] offset:51200
.LBB0_193:
	s_or_b64 exec, exec, s[12:13]
	v_add_u32_e32 v6, 0x200, v4
	v_cmp_gt_i32_e32 vcc, s93, v6
	s_and_saveexec_b64 s[12:13], vcc
	s_cbranch_execz .LBB0_195
	s_waitcnt vmcnt(0)
	ds_write_b128 v191, v[38:41] offset:51200
.LBB0_195:
	s_or_b64 exec, exec, s[12:13]
	v_add_u32_e32 v6, 0x400, v4
	v_cmp_gt_i32_e32 vcc, s93, v6
	s_and_saveexec_b64 s[12:13], vcc
	s_cbranch_execz .LBB0_197
	s_waitcnt vmcnt(0)
	ds_write_b128 v200, v[42:45] offset:51200
.LBB0_197:
	s_or_b64 exec, exec, s[12:13]
	v_add_u32_e32 v6, 0x600, v4
	v_cmp_gt_i32_e32 vcc, s93, v6
	s_and_saveexec_b64 s[12:13], vcc
	s_cbranch_execz .LBB0_199
	s_waitcnt vmcnt(0)
	ds_write_b128 v201, v[46:49] offset:51200
.LBB0_199:
	s_or_b64 exec, exec, s[12:13]
	v_add_u32_e32 v6, 0x800, v4
	v_cmp_gt_i32_e32 vcc, s93, v6
	s_and_saveexec_b64 s[12:13], vcc
	s_cbranch_execz .LBB0_201
	s_waitcnt vmcnt(0)
	ds_write_b128 v208, v[50:53] offset:51200
.LBB0_201:
	s_or_b64 exec, exec, s[12:13]
	v_add_u32_e32 v4, 0xa00, v4
	v_cmp_gt_i32_e32 vcc, s93, v4
	s_and_saveexec_b64 s[12:13], vcc
	s_cbranch_execz .LBB0_203
	s_waitcnt vmcnt(0)
	ds_write_b128 v209, v[54:57] offset:51200
